# attention tile loop: s_setprio 2 across the softmax (exp/sum/convert) stretch, back to 0 before the PV MFMAs
# speedup vs baseline: 1.0031x; 1.0011x over previous
.LBB0_557:
	s_setprio 2
	v_exp_f32_e32 v196, v80
	v_exp_f32_e32 v212, v64
	v_exp_f32_e32 v197, v81
	v_exp_f32_e32 v213, v65
	v_exp_f32_e32 v198, v82
	v_exp_f32_e32 v214, v66
	v_add_f32_e32 v229, v212, v196
	v_exp_f32_e32 v199, v83
	v_exp_f32_e32 v215, v67
	v_add_f32_e32 v230, v213, v197
	v_add_f32_e32 v229, v230, v229
	v_exp_f32_e32 v200, v84
	v_exp_f32_e32 v216, v68
	v_add_f32_e32 v228, v214, v198
	v_add_f32_e32 v229, v228, v229
	v_exp_f32_e32 v201, v85
	v_exp_f32_e32 v217, v69
	v_add_f32_e32 v230, v215, v199
	v_add_f32_e32 v229, v230, v229
	v_exp_f32_e32 v202, v86
	v_exp_f32_e32 v218, v70
	v_add_f32_e32 v228, v216, v200
	v_add_f32_e32 v229, v228, v229
	v_exp_f32_e32 v203, v87
	v_exp_f32_e32 v219, v71
	v_add_f32_e32 v230, v217, v201
	v_add_f32_e32 v229, v230, v229
	v_exp_f32_e32 v204, v88
	v_exp_f32_e32 v220, v72
	v_add_f32_e32 v228, v218, v202
	v_add_f32_e32 v229, v228, v229
	v_exp_f32_e32 v205, v89
	v_exp_f32_e32 v221, v73
	v_add_f32_e32 v230, v219, v203
	v_add_f32_e32 v229, v230, v229
	v_exp_f32_e32 v206, v90
	v_exp_f32_e32 v222, v74
	v_add_f32_e32 v228, v220, v204
	v_add_f32_e32 v229, v228, v229
	v_exp_f32_e32 v207, v91
	v_exp_f32_e32 v223, v75
	v_add_f32_e32 v230, v221, v205
	v_add_f32_e32 v229, v230, v229
	v_exp_f32_e32 v208, v92
	v_exp_f32_e32 v224, v76
	v_add_f32_e32 v228, v222, v206
	v_add_f32_e32 v229, v228, v229
	v_exp_f32_e32 v209, v93
	v_exp_f32_e32 v225, v77
	v_add_f32_e32 v230, v223, v207
	v_add_f32_e32 v229, v230, v229
	v_exp_f32_e32 v210, v94
	v_exp_f32_e32 v226, v78
	v_add_f32_e32 v228, v224, v208
	v_add_f32_e32 v229, v228, v229
	v_exp_f32_e32 v211, v95
	v_exp_f32_e32 v227, v79
	v_add_f32_e32 v230, v225, v209
	v_add_f32_e32 v229, v230, v229
	v_add_f32_e32 v228, v226, v210
	v_add_f32_e32 v229, v228, v229
	v_add_f32_e32 v230, v227, v211
	v_add_f32_e32 v231, v230, v229
	v_cmp_lt_f32_e32 vcc, 0x46000000, v231
	s_cbranch_vccnz .Lat_slow
	v_cvt_pk_bf16_f32 v64, v196, v197
	v_cvt_pk_bf16_f32 v65, v198, v199
	v_cvt_pk_bf16_f32 v66, v200, v201
	v_cvt_pk_bf16_f32 v67, v202, v203
	v_cvt_pk_bf16_f32 v68, v204, v205
	v_cvt_pk_bf16_f32 v69, v206, v207
	v_cvt_pk_bf16_f32 v70, v208, v209
	v_cvt_pk_bf16_f32 v71, v210, v211
	v_cvt_pk_bf16_f32 v72, v212, v213
	v_cvt_pk_bf16_f32 v73, v214, v215
	v_cvt_pk_bf16_f32 v74, v216, v217
	v_cvt_pk_bf16_f32 v75, v218, v219
	v_cvt_pk_bf16_f32 v76, v220, v221
	v_cvt_pk_bf16_f32 v77, v222, v223
	v_cvt_pk_bf16_f32 v78, v224, v225
	v_cvt_pk_bf16_f32 v79, v226, v227
	s_setprio 0
	v_add_f32_e32 v159, v159, v231
	s_waitcnt lgkmcnt(0)
	v_mfma_f32_32x32x16_bf16 v[32:47], v[148:151], v[64:67], v[32:47]
	v_mfma_f32_32x32x16_bf16 v[16:31], v[132:135], v[64:67], v[16:31]
	v_mfma_f32_32x32x16_bf16 v[32:47], v[144:147], v[68:71], v[32:47]
	v_mfma_f32_32x32x16_bf16 v[16:31], v[128:131], v[68:71], v[16:31]
	v_mfma_f32_32x32x16_bf16 v[32:47], v[140:143], v[72:75], v[32:47]
	v_mfma_f32_32x32x16_bf16 v[16:31], v[10:13], v[72:75], v[16:31]
	v_mfma_f32_32x32x16_bf16 v[32:47], v[136:139], v[76:79], v[32:47]
	v_mfma_f32_32x32x16_bf16 v[16:31], v[6:9], v[76:79], v[16:31]
